# lin_C2 epilogue: 8 output-norm gain vectors fetched once per item instead of one exposed round trip per store group
# baseline (speedup 1.0000x reference)
.LBB0_75:
	s_or_b64 exec, exec, s[14:15]
	s_ashr_i32 s14, s12, 7
	s_ashr_i32 s15, s14, 31
	s_lshl_b32 s13, s12, 8
	s_and_b32 s16, s13, 0x1f00
	s_lshl_b64 s[14:15], s[14:15], 13
	s_bfe_u32 s13, s12, 0x20005
	s_or_b32 s14, s14, s16
	v_lshl_add_u64 v[56:57], s[14:15], 0, v[0:1]
	v_lshl_add_u64 v[60:61], v[40:41], 0, s[14:15]
	s_lshl_b32 s14, s13, 9
	s_mov_b32 s15, s21
	v_lshl_or_b32 v4, s13, 7, v90
	v_lshl_add_u64 v[62:63], v[44:45], 0, s[14:15]
	v_lshlrev_b32_e32 v2, 2, v4
	v_readlane_b32 s14, v254, 50
	s_lshl_b32 s20, s13, 8
	v_lshl_add_u64 v[64:65], s[10:11], 0, v[2:3]
	global_load_dwordx4 v[184:187], v[64:65], off
	global_load_dwordx4 v[188:191], v[64:65], off offset:64
	global_load_dwordx4 v[192:195], v[64:65], off offset:128
	global_load_dwordx4 v[196:199], v[64:65], off offset:192
	global_load_dwordx4 v[200:203], v[64:65], off offset:256
	global_load_dwordx4 v[204:207], v[64:65], off offset:320
	global_load_dwordx4 v[230:233], v[64:65], off offset:384
	global_load_dwordx4 v[234:237], v[64:65], off offset:448
	v_lshlrev_b32_e32 v2, 1, v4
	v_readlane_b32 s15, v254, 51
	v_lshl_add_u64 v[58:59], v[38:39], 0, s[20:21]
	v_lshl_add_u64 v[66:67], v[54:55], 0, s[20:21]
	v_lshl_add_u64 v[68:69], s[14:15], 0, v[2:3]
	s_mov_b64 s[16:17], 0
	s_mov_b64 s[14:15], -1
	s_mov_b32 s20, 0x3c000
	s_mov_b32 s24, 0x78000
	s_mov_b32 s25, 0xb4000
.LBB0_76:
	v_lshl_add_u64 v[4:5], v[56:57], 0, s[16:17]
	v_mad_u64_u32 v[8:9], s[18:19], v4, s72, v[58:59]
	v_mov_b32_e32 v2, v9
	v_mad_u64_u32 v[10:11], s[18:19], v5, s72, v[2:3]
	v_mov_b32_e32 v9, v10
	v_add_co_u32_e32 v114, vcc, s20, v8
	s_nop 1
	v_addc_co_u32_e32 v115, vcc, 0, v10, vcc
	v_add_co_u32_e32 v116, vcc, s24, v8
	s_nop 1
	v_addc_co_u32_e32 v117, vcc, 0, v10, vcc
	v_add_co_u32_e32 v118, vcc, s25, v8
	s_nop 1
	v_addc_co_u32_e32 v119, vcc, 0, v10, vcc
	global_load_dwordx4 v[120:123], v[8:9], off
	global_load_dwordx4 v[124:127], v[114:115], off
	global_load_dwordx4 v[128:131], v[116:117], off
	global_load_dwordx4 v[132:135], v[118:119], off
	v_lshl_add_u64 v[98:99], v[60:61], 0, s[16:17]
	v_mad_u64_u32 v[70:71], s[16:17], v98, s72, v[66:67]
	v_mov_b32_e32 v2, v71
	v_lshlrev_b64 v[84:85], 11, v[98:99]
	v_add_u32_e32 v110, v43, v42
	v_mad_u64_u32 v[6:7], s[16:17], v99, s72, v[2:3]
	v_lshlrev_b64 v[98:99], 4, v[98:99]
	v_lshl_or_b32 v98, s13, 2, v98
	v_lshl_add_u64 v[4:5], v[62:63], 0, v[84:85]
	v_mov_b32_e32 v71, v6
	v_lshl_add_u64 v[100:101], s[6:7], 0, v[98:99]
	v_lshl_add_u64 v[98:99], s[0:1], 0, v[98:99]
	global_load_dwordx4 v[32:35], v[4:5], off
	global_load_dwordx2 v[86:87], v[70:71], off offset:3072
	global_load_dwordx4 v[28:31], v[4:5], off offset:64
	global_load_dwordx2 v[82:83], v[70:71], off offset:3104
	global_load_dwordx4 v[24:27], v[4:5], off offset:128
	global_load_dwordx2 v[80:81], v[70:71], off offset:3136
	global_load_dwordx4 v[20:23], v[4:5], off offset:192
	global_load_dwordx2 v[78:79], v[70:71], off offset:3168
	global_load_dwordx4 v[16:19], v[4:5], off offset:256
	global_load_dwordx2 v[76:77], v[70:71], off offset:3200
	global_load_dwordx4 v[12:15], v[4:5], off offset:320
	global_load_dwordx2 v[74:75], v[70:71], off offset:3232
	global_load_dwordx4 v[8:11], v[4:5], off offset:384
	global_load_dwordx2 v[72:73], v[70:71], off offset:3264
	s_nop 0
	global_load_dwordx4 v[4:7], v[4:5], off offset:448
	s_nop 0
	global_load_dwordx2 v[70:71], v[70:71], off offset:3296
	s_nop 0
	global_load_dword v2, v[100:101], off
	global_load_dword v97, v[98:99], off
	s_waitcnt lgkmcnt(0)
	s_barrier
	s_waitcnt vmcnt(21)
	ds_write_b128 v96, v[120:123] offset:34816
	s_waitcnt vmcnt(20)
	ds_write_b128 v96, v[124:127] offset:43520
	s_waitcnt vmcnt(19)
	ds_write_b128 v96, v[128:131] offset:52224
	s_waitcnt vmcnt(18)
	ds_write_b128 v96, v[132:135] offset:60928
	s_waitcnt lgkmcnt(0)
	s_barrier
	ds_read_b128 v[98:101], v110 offset:34816
	ds_read_b128 v[102:105], v110 offset:34880
	ds_read_b128 v[106:109], v110 offset:34944
	ds_read_b128 v[110:113], v110 offset:35008
	ds_read_b128 v[114:117], v93
	ds_read_b128 v[118:121], v93 offset:64
	ds_read_b128 v[122:125], v93 offset:4416
	s_waitcnt lgkmcnt(2)
	v_mfma_f32_16x16x32_bf16 v[114:117], v[114:117], v[98:101], 0
	ds_read_b128 v[126:129], v93 offset:8768
	ds_read_b128 v[130:133], v93 offset:13120
	ds_read_b128 v[134:137], v93 offset:17472
	s_waitcnt lgkmcnt(4)
	v_mfma_f32_16x16x32_bf16 v[114:117], v[118:121], v[102:105], v[114:117]
	ds_read_b128 v[118:121], v93 offset:128
	ds_read_b128 v[138:141], v93 offset:21824
	ds_read_b128 v[142:145], v93 offset:26176
	s_waitcnt lgkmcnt(2)
	v_mfma_f32_16x16x32_bf16 v[114:117], v[118:121], v[106:109], v[114:117]
	ds_read_b128 v[118:121], v93 offset:192
	s_waitcnt vmcnt(1)
	v_mul_f32_e32 v2, 0x3db504f3, v2
	s_waitcnt lgkmcnt(0)
	v_mfma_f32_16x16x32_bf16 v[114:117], v[118:121], v[110:113], v[114:117]
	ds_read_b128 v[118:121], v93 offset:4352
	s_waitcnt lgkmcnt(0)
	v_mfma_f32_16x16x32_bf16 v[118:121], v[118:121], v[98:101], 0
	s_nop 4
	v_fma_f32 v32, v2, v114, v32
	v_fma_f32 v33, v2, v115, v33
	v_pk_fma_f32 v[34:35], v[2:3], v[116:117], v[34:35] op_sel_hi:[0,1,1]
	v_mfma_f32_16x16x32_bf16 v[118:121], v[122:125], v[102:105], v[118:121]
	ds_read_b128 v[122:125], v93 offset:4480
	s_waitcnt lgkmcnt(0)
	v_mfma_f32_16x16x32_bf16 v[118:121], v[122:125], v[106:109], v[118:121]
	ds_read_b128 v[122:125], v93 offset:4544
	s_waitcnt lgkmcnt(0)
	v_mfma_f32_16x16x32_bf16 v[118:121], v[122:125], v[110:113], v[118:121]
	ds_read_b128 v[122:125], v93 offset:8704
	s_waitcnt lgkmcnt(0)
	v_mfma_f32_16x16x32_bf16 v[122:125], v[122:125], v[98:101], 0
	v_mfma_f32_16x16x32_bf16 v[122:125], v[126:129], v[102:105], v[122:125]
	ds_read_b128 v[126:129], v93 offset:8832
	s_waitcnt lgkmcnt(0)
	v_mfma_f32_16x16x32_bf16 v[122:125], v[126:129], v[106:109], v[122:125]
	ds_read_b128 v[126:129], v93 offset:8896
	s_waitcnt lgkmcnt(0)
	v_mfma_f32_16x16x32_bf16 v[122:125], v[126:129], v[110:113], v[122:125]
	ds_read_b128 v[126:129], v93 offset:13056
	s_nop 6
	v_pk_fma_f32 v[24:25], v[2:3], v[122:123], v[24:25] op_sel_hi:[0,1,1]
	s_waitcnt lgkmcnt(0)
	v_mfma_f32_16x16x32_bf16 v[126:129], v[126:129], v[98:101], 0
	v_mfma_f32_16x16x32_bf16 v[126:129], v[130:133], v[102:105], v[126:129]
	ds_read_b128 v[130:133], v93 offset:13184
	s_waitcnt lgkmcnt(0)
	v_mfma_f32_16x16x32_bf16 v[126:129], v[130:133], v[106:109], v[126:129]
	ds_read_b128 v[130:133], v93 offset:13248
	s_waitcnt lgkmcnt(0)
	v_mfma_f32_16x16x32_bf16 v[126:129], v[130:133], v[110:113], v[126:129]
	ds_read_b128 v[130:133], v93 offset:17408
	s_waitcnt lgkmcnt(0)
	v_mfma_f32_16x16x32_bf16 v[130:133], v[130:133], v[98:101], 0
	v_mfma_f32_16x16x32_bf16 v[130:133], v[134:137], v[102:105], v[130:133]
	ds_read_b128 v[134:137], v93 offset:17536
	s_waitcnt lgkmcnt(0)
	v_mfma_f32_16x16x32_bf16 v[130:133], v[134:137], v[106:109], v[130:133]
	ds_read_b128 v[134:137], v93 offset:17600
	s_waitcnt lgkmcnt(0)
	v_mfma_f32_16x16x32_bf16 v[130:133], v[134:137], v[110:113], v[130:133]
	ds_read_b128 v[134:137], v93 offset:21760
	s_waitcnt lgkmcnt(0)
	v_mfma_f32_16x16x32_bf16 v[134:137], v[134:137], v[98:101], 0
	v_mfma_f32_16x16x32_bf16 v[134:137], v[138:141], v[102:105], v[134:137]
	ds_read_b128 v[138:141], v93 offset:21888
	s_waitcnt lgkmcnt(0)
	v_mfma_f32_16x16x32_bf16 v[134:137], v[138:141], v[106:109], v[134:137]
	ds_read_b128 v[138:141], v93 offset:21952
	s_waitcnt lgkmcnt(0)
	v_mfma_f32_16x16x32_bf16 v[134:137], v[138:141], v[110:113], v[134:137]
	ds_read_b128 v[138:141], v93 offset:26112
	s_nop 6
	v_pk_fma_f32 v[12:13], v[2:3], v[134:135], v[12:13] op_sel_hi:[0,1,1]
	s_waitcnt lgkmcnt(0)
	v_mfma_f32_16x16x32_bf16 v[138:141], v[138:141], v[98:101], 0
	v_mfma_f32_16x16x32_bf16 v[138:141], v[142:145], v[102:105], v[138:141]
	ds_read_b128 v[142:145], v93 offset:26240
	s_waitcnt lgkmcnt(0)
	v_mfma_f32_16x16x32_bf16 v[138:141], v[142:145], v[106:109], v[138:141]
	ds_read_b128 v[142:145], v93 offset:26304
	s_waitcnt lgkmcnt(0)
	v_mfma_f32_16x16x32_bf16 v[138:141], v[142:145], v[110:113], v[138:141]
	ds_read_b128 v[142:145], v93 offset:30464
	s_waitcnt lgkmcnt(0)
	v_mfma_f32_16x16x32_bf16 v[98:101], v[142:145], v[98:101], 0
	ds_read_b128 v[142:145], v93 offset:30528
	s_waitcnt lgkmcnt(0)
	v_mfma_f32_16x16x32_bf16 v[98:101], v[142:145], v[102:105], v[98:101]
	ds_read_b128 v[102:105], v93 offset:30592
	s_waitcnt lgkmcnt(0)
	v_mfma_f32_16x16x32_bf16 v[98:101], v[102:105], v[106:109], v[98:101]
	ds_read_b128 v[102:105], v93 offset:30656
	s_waitcnt lgkmcnt(0)
	v_mfma_f32_16x16x32_bf16 v[98:101], v[102:105], v[110:113], v[98:101]
	ds_read_b128 v[102:105], v94 offset:34816
	ds_read_b128 v[106:109], v94 offset:34832
	ds_read_b128 v[110:113], v94 offset:34848
	ds_read_b128 v[142:145], v94 offset:34864
	ds_read_b128 v[146:149], v95
	ds_read_b128 v[150:153], v95 offset:16
	ds_read_b128 v[154:157], v95 offset:32
	ds_read_b128 v[158:161], v95 offset:48
	s_waitcnt lgkmcnt(7)
	v_and_b32_e32 v166, 0xffff0000, v102
	s_waitcnt lgkmcnt(6)
	v_and_b32_e32 v167, 0xffff0000, v106
	v_lshlrev_b32_e32 v163, 16, v106
	s_waitcnt lgkmcnt(1)
	v_mov_b32_e32 v165, v154
	v_mov_b32_e32 v154, v147
	v_lshlrev_b32_e32 v162, 16, v102
	v_mov_b32_e32 v164, v146
	v_pk_mul_f32 v[146:147], v[154:155], v[166:167]
	v_lshlrev_b32_e32 v155, 16, v107
	v_pk_fma_f32 v[146:147], v[164:165], v[162:163], v[146:147]
	v_lshlrev_b32_e32 v154, 16, v103
	v_mov_b32_e32 v162, v148
	v_mov_b32_e32 v163, v156
	v_pk_fma_f32 v[146:147], v[162:163], v[154:155], v[146:147]
	v_and_b32_e32 v107, 0xffff0000, v107
	v_and_b32_e32 v106, 0xffff0000, v103
	v_mov_b32_e32 v156, v149
	v_pk_fma_f32 v[102:103], v[156:157], v[106:107], v[146:147]
	v_lshlrev_b32_e32 v107, 16, v108
	v_lshlrev_b32_e32 v106, 16, v104
	v_mov_b32_e32 v146, v150
	s_waitcnt lgkmcnt(0)
	v_mov_b32_e32 v147, v158
	v_pk_fma_f32 v[102:103], v[146:147], v[106:107], v[102:103]
	v_and_b32_e32 v107, 0xffff0000, v108
	v_and_b32_e32 v106, 0xffff0000, v104
	v_mov_b32_e32 v158, v151
	v_pk_fma_f32 v[102:103], v[158:159], v[106:107], v[102:103]
	v_lshlrev_b32_e32 v107, 16, v109
	v_lshlrev_b32_e32 v106, 16, v105
	v_mov_b32_e32 v146, v152
	v_mov_b32_e32 v147, v160
	v_pk_fma_f32 v[102:103], v[146:147], v[106:107], v[102:103]
	v_and_b32_e32 v107, 0xffff0000, v109
	v_and_b32_e32 v106, 0xffff0000, v105
	v_mov_b32_e32 v160, v153
	v_pk_fma_f32 v[102:103], v[160:161], v[106:107], v[102:103]
	v_and_b32_e32 v159, 0xffff0000, v142
	v_add_f32_e32 v102, 0, v102
	v_add_f32_e32 v160, v102, v103
	ds_read_b128 v[102:105], v95 offset:80
	ds_read_b128 v[106:109], v95 offset:112
	ds_read_b128 v[146:149], v95 offset:64
	ds_read_b128 v[150:153], v95 offset:96
	v_and_b32_e32 v158, 0xffff0000, v110
	v_lshlrev_b32_e32 v155, 16, v142
	v_lshlrev_b32_e32 v154, 16, v110
	s_waitcnt lgkmcnt(1)
	v_mov_b32_e32 v156, v146
	s_waitcnt lgkmcnt(0)
	v_mov_b32_e32 v157, v150
	v_mov_b32_e32 v150, v147
	v_pk_mul_f32 v[146:147], v[150:151], v[158:159]
	v_lshlrev_b32_e32 v151, 16, v143
	v_pk_fma_f32 v[146:147], v[156:157], v[154:155], v[146:147]
	v_lshlrev_b32_e32 v150, 16, v111
	v_mov_b32_e32 v154, v148
	v_mov_b32_e32 v155, v152
	v_pk_fma_f32 v[146:147], v[154:155], v[150:151], v[146:147]
	v_and_b32_e32 v143, 0xffff0000, v143
	v_and_b32_e32 v142, 0xffff0000, v111
	v_mov_b32_e32 v152, v149
	v_pk_fma_f32 v[110:111], v[152:153], v[142:143], v[146:147]
	v_lshlrev_b32_e32 v143, 16, v144
	v_lshlrev_b32_e32 v142, 16, v112
	v_mov_b32_e32 v146, v102
	v_mov_b32_e32 v147, v106
	v_pk_fma_f32 v[110:111], v[146:147], v[142:143], v[110:111]
	v_and_b32_e32 v143, 0xffff0000, v144
	v_and_b32_e32 v142, 0xffff0000, v112
	v_mov_b32_e32 v106, v103
	v_pk_fma_f32 v[102:103], v[106:107], v[142:143], v[110:111]
	v_lshlrev_b32_e32 v107, 16, v145
	v_lshlrev_b32_e32 v106, 16, v113
	v_mov_b32_e32 v110, v104
	v_mov_b32_e32 v111, v108
	v_pk_fma_f32 v[102:103], v[110:111], v[106:107], v[102:103]
	v_and_b32_e32 v107, 0xffff0000, v145
	v_and_b32_e32 v106, 0xffff0000, v113
	v_mov_b32_e32 v108, v105
	v_pk_fma_f32 v[102:103], v[108:109], v[106:107], v[102:103]
	v_pk_fma_f32 v[112:113], v[2:3], v[130:131], v[16:17] op_sel_hi:[0,1,1]
	v_add_f32_e32 v102, v160, v102
	v_add_f32_e32 v102, v102, v103
	ds_bpermute_b32 v103, v91, v102
	v_pk_fma_f32 v[16:17], v[2:3], v[132:133], v[18:19] op_sel_hi:[0,1,1]
	v_pk_fma_f32 v[98:99], v[2:3], v[98:99], v[4:5] op_sel_hi:[0,1,1]
	v_pk_fma_f32 v[4:5], v[2:3], v[100:101], v[6:7] op_sel_hi:[0,1,1]
	s_waitcnt lgkmcnt(0)
	v_add_f32_e32 v102, v102, v103
	ds_bpermute_b32 v103, v92, v102
	s_waitcnt lgkmcnt(0)
	v_add_f32_e32 v102, v102, v103
	s_waitcnt vmcnt(0)
	v_fmac_f32_e32 v97, v2, v102
	v_max_f32_e64 v97, |v97|, 1.0
	v_div_scale_f32 v102, s[16:17], v97, v97, 1.0
	v_rcp_f32_e32 v103, v102
	s_mov_b64 s[16:17], 0x80
	v_fma_f32 v104, -v102, v103, 1.0
	v_fmac_f32_e32 v103, v104, v103
	v_div_scale_f32 v104, vcc, 1.0, v97, 1.0
	v_mul_f32_e32 v105, v104, v103
	v_fma_f32 v106, -v102, v105, v104
	v_fmac_f32_e32 v105, v106, v103
	v_fma_f32 v102, -v102, v105, v104
	v_div_fmas_f32 v102, v102, v103, v105
	v_div_fixup_f32 v102, v102, v97, 1.0
	v_pk_mul_f32 v[106:107], v[32:33], v[102:103] op_sel_hi:[1,0]
	v_pk_fma_f32 v[32:33], v[2:3], v[118:119], v[28:29] op_sel_hi:[0,1,1]
	v_pk_fma_f32 v[28:29], v[2:3], v[120:121], v[30:31] op_sel_hi:[0,1,1]
	v_pk_mul_f32 v[30:31], v[32:33], v[102:103] op_sel_hi:[1,0]
	v_pk_mul_f32 v[104:105], v[34:35], v[102:103] op_sel_hi:[1,0]
	v_pk_mul_f32 v[28:29], v[28:29], v[102:103] op_sel_hi:[1,0]
	v_mov_b32_e32 v34, v107
	v_mov_b32_e32 v35, v31
	v_mov_b32_e32 v32, v106
	v_mov_b32_e32 v33, v30
	v_pk_mul_f32 v[34:35], v[34:35], v[34:35]
	v_mov_b32_e32 v108, v105
	v_mov_b32_e32 v109, v29
	v_pk_fma_f32 v[32:33], v[32:33], v[32:33], v[34:35]
	v_mov_b32_e32 v34, v104
	v_mov_b32_e32 v35, v28
	v_pk_mul_f32 v[108:109], v[108:109], v[108:109]
	v_pk_mul_f32 v[16:17], v[16:17], v[102:103] op_sel_hi:[1,0]
	v_pk_fma_f32 v[34:35], v[34:35], v[34:35], v[108:109]
	v_pk_mul_f32 v[18:19], v[112:113], v[102:103] op_sel_hi:[1,0]
	v_pk_add_f32 v[32:33], v[32:33], v[34:35]
	v_pk_fma_f32 v[34:35], v[2:3], v[124:125], v[26:27] op_sel_hi:[0,1,1]
	v_pk_mul_f32 v[26:27], v[24:25], v[102:103] op_sel_hi:[1,0]
	v_pk_mul_f32 v[24:25], v[34:35], v[102:103] op_sel_hi:[1,0]
	v_pk_mul_f32 v[108:109], v[26:27], v[26:27]
	v_pk_mul_f32 v[34:35], v[24:25], v[24:25]
	v_pk_add_f32 v[32:33], v[32:33], v[32:33] op_sel_hi:[0,1]
	v_pk_mov_b32 v[110:111], v[108:109], v[34:35] op_sel:[1,0]
	v_mov_b32_e32 v109, v35
	v_pk_add_f32 v[34:35], v[110:111], v[108:109]
	v_pk_fma_f32 v[108:109], v[2:3], v[126:127], v[20:21] op_sel_hi:[0,1,1]
	v_pk_fma_f32 v[20:21], v[2:3], v[128:129], v[22:23] op_sel_hi:[0,1,1]
	v_pk_mul_f32 v[22:23], v[108:109], v[102:103] op_sel_hi:[1,0]
	v_pk_mul_f32 v[20:21], v[20:21], v[102:103] op_sel_hi:[1,0]
	v_mul_f32_e32 v32, v22, v22
	v_pk_add_f32 v[34:35], v[34:35], v[34:35] op_sel_hi:[0,1]
	v_pk_fma_f32 v[108:109], v[22:23], v[22:23], v[32:33] op_sel_hi:[1,1,0]
	v_mul_f32_e32 v32, v20, v20
	v_pk_fma_f32 v[110:111], v[20:21], v[20:21], v[32:33] op_sel_hi:[1,1,0]
	v_mul_f32_e32 v34, v16, v16
	v_mul_f32_e32 v32, v17, v17
	v_mul_f32_e32 v108, v18, v18
	v_mul_f32_e32 v110, v19, v19
	v_pk_add_f32 v[32:33], v[34:35], v[32:33]
	v_pk_fma_f32 v[34:35], v[2:3], v[136:137], v[14:15] op_sel_hi:[0,1,1]
	v_pk_add_f32 v[108:109], v[108:109], v[110:111]
	v_pk_mul_f32 v[14:15], v[12:13], v[102:103] op_sel_hi:[1,0]
	v_pk_mul_f32 v[12:13], v[34:35], v[102:103] op_sel_hi:[1,0]
	v_pk_add_f32 v[32:33], v[108:109], v[32:33]
	v_pk_mul_f32 v[34:35], v[12:13], v[12:13]
	v_pk_mul_f32 v[108:109], v[14:15], v[14:15]
	v_pk_add_f32 v[32:33], v[32:33], v[32:33] op_sel_hi:[0,1]
	v_pk_mov_b32 v[110:111], v[108:109], v[34:35] op_sel:[1,0]
	v_mov_b32_e32 v109, v35
	v_pk_add_f32 v[34:35], v[110:111], v[108:109]
	v_pk_fma_f32 v[108:109], v[2:3], v[138:139], v[8:9] op_sel_hi:[0,1,1]
	v_pk_fma_f32 v[8:9], v[2:3], v[140:141], v[10:11] op_sel_hi:[0,1,1]
	v_pk_mul_f32 v[10:11], v[108:109], v[102:103] op_sel_hi:[1,0]
	v_pk_mul_f32 v[8:9], v[8:9], v[102:103] op_sel_hi:[1,0]
	v_mul_f32_e32 v32, v10, v10
	v_pk_fma_f32 v[108:109], v[10:11], v[10:11], v[32:33] op_sel_hi:[1,1,0]
	v_mul_f32_e32 v32, v8, v8
	v_pk_add_f32 v[34:35], v[34:35], v[34:35] op_sel_hi:[0,1]
	v_pk_fma_f32 v[110:111], v[8:9], v[8:9], v[32:33] op_sel_hi:[1,1,0]
	v_pk_mul_f32 v[4:5], v[4:5], v[102:103] op_sel_hi:[1,0]
	v_pk_mul_f32 v[6:7], v[98:99], v[102:103] op_sel_hi:[1,0]
	v_mul_f32_e32 v34, v4, v4
	v_mul_f32_e32 v108, v6, v6
	v_mul_f32_e32 v110, v7, v7
	v_mul_f32_e32 v32, v5, v5
	v_pk_add_f32 v[98:99], v[108:109], v[110:111]
	v_pk_add_f32 v[32:33], v[34:35], v[32:33]
	v_lshlrev_b32_e32 v97, 16, v86
	v_pk_add_f32 v[32:33], v[98:99], v[32:33]
	v_and_b32_e32 v86, 0xffff0000, v86
	v_add_f32_e32 v2, v32, v33
	ds_bpermute_b32 v32, v91, v2
	v_mul_f32_e32 v86, 0xbfb8aa3b, v86
	v_exp_f32_e32 v86, v86
	v_mul_f32_e32 v97, 0xbfb8aa3b, v97
	v_exp_f32_e32 v97, v97
	s_waitcnt lgkmcnt(0)
	v_add_f32_e32 v2, v2, v32
	ds_bpermute_b32 v32, v92, v2
	v_add_f32_e32 v86, 1.0, v86
	v_rcp_f32_e32 v99, v86
	v_lshlrev_b32_e32 v86, 16, v87
	v_and_b32_e32 v87, 0xffff0000, v87
	s_waitcnt lgkmcnt(0)
	v_add_f32_e32 v2, v2, v32
	v_fmamk_f32 v2, v2, 0x3c000000, v172
	v_cmp_gt_f32_e32 vcc, s33, v2
	v_mul_f32_e32 v32, 0x4b800000, v2
	v_mul_f32_e32 v86, 0xbfb8aa3b, v86
	v_cndmask_b32_e32 v2, v2, v32, vcc
	v_rsq_f32_e32 v2, v2
	v_mul_f32_e32 v87, 0xbfb8aa3b, v87
	v_exp_f32_e32 v86, v86
	v_exp_f32_e32 v87, v87
	v_mul_f32_e32 v32, 0x45800000, v2
	v_cndmask_b32_e32 v2, v2, v32, vcc
	v_add_f32_e32 v97, 1.0, v97
	v_rcp_f32_e32 v98, v97
	v_add_f32_e32 v86, 1.0, v86
	v_add_f32_e32 v87, 1.0, v87
	v_pk_mul_f32 v[100:101], v[106:107], v[2:3] op_sel_hi:[1,0]
	v_rcp_f32_e32 v86, v86
	v_rcp_f32_e32 v87, v87
	v_pk_mul_f32 v[30:31], v[30:31], v[2:3] op_sel_hi:[1,0]
	v_pk_mul_f32 v[28:29], v[28:29], v[2:3] op_sel_hi:[1,0]
	v_pk_mul_f32 v[26:27], v[26:27], v[2:3] op_sel_hi:[1,0]
	v_pk_mul_f32 v[24:25], v[24:25], v[2:3] op_sel_hi:[1,0]
	v_pk_mul_f32 v[22:23], v[22:23], v[2:3] op_sel_hi:[1,0]
	v_pk_mul_f32 v[20:21], v[20:21], v[2:3] op_sel_hi:[1,0]
	v_pk_mul_f32 v[18:19], v[18:19], v[2:3] op_sel_hi:[1,0]
	v_pk_mul_f32 v[16:17], v[16:17], v[2:3] op_sel_hi:[1,0]
	v_pk_mul_f32 v[14:15], v[14:15], v[2:3] op_sel_hi:[1,0]
	v_pk_mul_f32 v[12:13], v[12:13], v[2:3] op_sel_hi:[1,0]
	v_pk_mul_f32 v[10:11], v[10:11], v[2:3] op_sel_hi:[1,0]
	v_pk_mul_f32 v[8:9], v[8:9], v[2:3] op_sel_hi:[1,0]
	v_pk_mul_f32 v[6:7], v[6:7], v[2:3] op_sel_hi:[1,0]
	v_pk_mul_f32 v[4:5], v[4:5], v[2:3] op_sel_hi:[1,0]
	s_andn2_b64 vcc, exec, s[14:15]
	s_mov_b64 s[14:15], 0
	s_waitcnt vmcnt(0)
	v_mov_b64_e32 v[32:33], v[184:185]
	v_mov_b64_e32 v[34:35], v[186:187]
	v_pk_mul_f32 v[32:33], v[32:33], v[100:101]
	s_nop 0
	v_pk_mul_f32 v[32:33], v[98:99], v[32:33]
	v_pk_mul_f32 v[98:99], v[104:105], v[2:3] op_sel_hi:[1,0]
	v_cvt_pk_bf16_f32 v32, v32, v33
	v_pk_mul_f32 v[34:35], v[34:35], v[98:99]
	s_nop 0
	v_pk_mul_f32 v[34:35], v[86:87], v[34:35]
	s_nop 0
	v_cvt_pk_bf16_f32 v33, v34, v35
	v_lshl_add_u64 v[34:35], v[68:69], 0, v[84:85]
	global_store_dwordx2 v[34:35], v[32:33], off
	v_lshlrev_b32_e32 v32, 16, v82
	v_and_b32_e32 v33, 0xffff0000, v82
	v_mul_f32_e32 v32, 0xbfb8aa3b, v32
	v_mul_f32_e32 v33, 0xbfb8aa3b, v33
	v_exp_f32_e32 v32, v32
	v_exp_f32_e32 v33, v33
	v_add_f32_e32 v32, 1.0, v32
	v_add_f32_e32 v33, 1.0, v33
	v_rcp_f32_e32 v32, v32
	v_rcp_f32_e32 v33, v33
	v_mov_b64_e32 v[84:85], v[188:189]
	v_mov_b64_e32 v[86:87], v[190:191]
	v_pk_mul_f32 v[30:31], v[84:85], v[30:31]
	s_nop 0
	v_pk_mul_f32 v[30:31], v[32:33], v[30:31]
	v_lshlrev_b32_e32 v32, 16, v83
	v_and_b32_e32 v33, 0xffff0000, v83
	v_mul_f32_e32 v32, 0xbfb8aa3b, v32
	v_mul_f32_e32 v33, 0xbfb8aa3b, v33
	v_exp_f32_e32 v32, v32
	v_exp_f32_e32 v33, v33
	v_pk_mul_f32 v[28:29], v[86:87], v[28:29]
	v_cvt_pk_bf16_f32 v30, v30, v31
	v_add_f32_e32 v32, 1.0, v32
	v_add_f32_e32 v33, 1.0, v33
	v_rcp_f32_e32 v32, v32
	v_rcp_f32_e32 v33, v33
	s_nop 0
	v_pk_mul_f32 v[28:29], v[32:33], v[28:29]
	s_nop 0
	v_cvt_pk_bf16_f32 v31, v28, v29
	global_store_dwordx2 v[34:35], v[30:31], off offset:32
	v_lshlrev_b32_e32 v32, 16, v80
	v_and_b32_e32 v33, 0xffff0000, v80
	v_mul_f32_e32 v32, 0xbfb8aa3b, v32
	v_mul_f32_e32 v33, 0xbfb8aa3b, v33
	v_exp_f32_e32 v32, v32
	v_exp_f32_e32 v33, v33
	v_add_f32_e32 v32, 1.0, v32
	v_add_f32_e32 v33, 1.0, v33
	v_rcp_f32_e32 v32, v32
	v_rcp_f32_e32 v33, v33
	v_mov_b64_e32 v[28:29], v[192:193]
	v_mov_b64_e32 v[30:31], v[194:195]
	v_pk_mul_f32 v[26:27], v[28:29], v[26:27]
	v_lshlrev_b32_e32 v28, 16, v81
	v_and_b32_e32 v29, 0xffff0000, v81
	v_mul_f32_e32 v28, 0xbfb8aa3b, v28
	v_mul_f32_e32 v29, 0xbfb8aa3b, v29
	v_exp_f32_e32 v28, v28
	v_exp_f32_e32 v29, v29
	v_pk_mul_f32 v[24:25], v[30:31], v[24:25]
	v_pk_mul_f32 v[26:27], v[32:33], v[26:27]
	v_add_f32_e32 v28, 1.0, v28
	v_add_f32_e32 v29, 1.0, v29
	v_rcp_f32_e32 v28, v28
	v_rcp_f32_e32 v29, v29
	v_cvt_pk_bf16_f32 v26, v26, v27
	v_pk_mul_f32 v[24:25], v[28:29], v[24:25]
	s_nop 0
	v_cvt_pk_bf16_f32 v27, v24, v25
	global_store_dwordx2 v[34:35], v[26:27], off offset:64
	v_lshlrev_b32_e32 v28, 16, v78
	v_and_b32_e32 v29, 0xffff0000, v78
	v_mul_f32_e32 v28, 0xbfb8aa3b, v28
	v_mul_f32_e32 v29, 0xbfb8aa3b, v29
	v_exp_f32_e32 v28, v28
	v_exp_f32_e32 v29, v29
	v_add_f32_e32 v28, 1.0, v28
	v_add_f32_e32 v29, 1.0, v29
	v_rcp_f32_e32 v28, v28
	v_rcp_f32_e32 v29, v29
	v_mov_b64_e32 v[24:25], v[196:197]
	v_mov_b64_e32 v[26:27], v[198:199]
	v_pk_mul_f32 v[22:23], v[24:25], v[22:23]
	v_lshlrev_b32_e32 v24, 16, v79
	v_and_b32_e32 v25, 0xffff0000, v79
	v_mul_f32_e32 v24, 0xbfb8aa3b, v24
	v_mul_f32_e32 v25, 0xbfb8aa3b, v25
	v_exp_f32_e32 v24, v24
	v_exp_f32_e32 v25, v25
	v_pk_mul_f32 v[20:21], v[26:27], v[20:21]
	v_pk_mul_f32 v[22:23], v[28:29], v[22:23]
	v_add_f32_e32 v24, 1.0, v24
	v_add_f32_e32 v25, 1.0, v25
	v_rcp_f32_e32 v24, v24
	v_rcp_f32_e32 v25, v25
	v_cvt_pk_bf16_f32 v22, v22, v23
	v_pk_mul_f32 v[20:21], v[24:25], v[20:21]
	s_nop 0
	v_cvt_pk_bf16_f32 v23, v20, v21
	global_store_dwordx2 v[34:35], v[22:23], off offset:96
	v_lshlrev_b32_e32 v24, 16, v76
	v_and_b32_e32 v25, 0xffff0000, v76
	v_mul_f32_e32 v24, 0xbfb8aa3b, v24
	v_mul_f32_e32 v25, 0xbfb8aa3b, v25
	v_exp_f32_e32 v24, v24
	v_exp_f32_e32 v25, v25
	v_add_f32_e32 v24, 1.0, v24
	v_add_f32_e32 v25, 1.0, v25
	v_rcp_f32_e32 v24, v24
	v_rcp_f32_e32 v25, v25
	v_mov_b64_e32 v[20:21], v[200:201]
	v_mov_b64_e32 v[22:23], v[202:203]
	v_pk_mul_f32 v[18:19], v[20:21], v[18:19]
	v_lshlrev_b32_e32 v20, 16, v77
	v_and_b32_e32 v21, 0xffff0000, v77
	v_mul_f32_e32 v20, 0xbfb8aa3b, v20
	v_mul_f32_e32 v21, 0xbfb8aa3b, v21
	v_exp_f32_e32 v20, v20
	v_exp_f32_e32 v21, v21
	v_pk_mul_f32 v[16:17], v[22:23], v[16:17]
	v_pk_mul_f32 v[18:19], v[24:25], v[18:19]
	v_add_f32_e32 v20, 1.0, v20
	v_add_f32_e32 v21, 1.0, v21
	v_rcp_f32_e32 v20, v20
	v_rcp_f32_e32 v21, v21
	v_cvt_pk_bf16_f32 v18, v18, v19
	v_pk_mul_f32 v[16:17], v[20:21], v[16:17]
	s_nop 0
	v_cvt_pk_bf16_f32 v19, v16, v17
	global_store_dwordx2 v[34:35], v[18:19], off offset:128
	v_lshlrev_b32_e32 v20, 16, v74
	v_and_b32_e32 v21, 0xffff0000, v74
	v_mul_f32_e32 v20, 0xbfb8aa3b, v20
	v_mul_f32_e32 v21, 0xbfb8aa3b, v21
	v_exp_f32_e32 v20, v20
	v_exp_f32_e32 v21, v21
	v_add_f32_e32 v20, 1.0, v20
	v_add_f32_e32 v21, 1.0, v21
	v_rcp_f32_e32 v20, v20
	v_rcp_f32_e32 v21, v21
	v_mov_b64_e32 v[16:17], v[204:205]
	v_mov_b64_e32 v[18:19], v[206:207]
	v_pk_mul_f32 v[14:15], v[16:17], v[14:15]
	v_lshlrev_b32_e32 v16, 16, v75
	v_and_b32_e32 v17, 0xffff0000, v75
	v_mul_f32_e32 v16, 0xbfb8aa3b, v16
	v_mul_f32_e32 v17, 0xbfb8aa3b, v17
	v_exp_f32_e32 v16, v16
	v_exp_f32_e32 v17, v17
	v_pk_mul_f32 v[12:13], v[18:19], v[12:13]
	v_pk_mul_f32 v[14:15], v[20:21], v[14:15]
	v_add_f32_e32 v16, 1.0, v16
	v_add_f32_e32 v17, 1.0, v17
	v_rcp_f32_e32 v16, v16
	v_rcp_f32_e32 v17, v17
	v_cvt_pk_bf16_f32 v14, v14, v15
	v_pk_mul_f32 v[12:13], v[16:17], v[12:13]
	s_nop 0
	v_cvt_pk_bf16_f32 v15, v12, v13
	global_store_dwordx2 v[34:35], v[14:15], off offset:160
	v_lshlrev_b32_e32 v16, 16, v72
	v_and_b32_e32 v17, 0xffff0000, v72
	v_mul_f32_e32 v16, 0xbfb8aa3b, v16
	v_mul_f32_e32 v17, 0xbfb8aa3b, v17
	v_exp_f32_e32 v16, v16
	v_exp_f32_e32 v17, v17
	v_add_f32_e32 v16, 1.0, v16
	v_add_f32_e32 v17, 1.0, v17
	v_rcp_f32_e32 v16, v16
	v_rcp_f32_e32 v17, v17
	v_mov_b64_e32 v[12:13], v[230:231]
	v_mov_b64_e32 v[14:15], v[232:233]
	v_pk_mul_f32 v[10:11], v[12:13], v[10:11]
	v_lshlrev_b32_e32 v12, 16, v73
	v_and_b32_e32 v13, 0xffff0000, v73
	v_mul_f32_e32 v12, 0xbfb8aa3b, v12
	v_mul_f32_e32 v13, 0xbfb8aa3b, v13
	v_exp_f32_e32 v12, v12
	v_exp_f32_e32 v13, v13
	v_pk_mul_f32 v[8:9], v[14:15], v[8:9]
	v_pk_mul_f32 v[10:11], v[16:17], v[10:11]
	v_add_f32_e32 v12, 1.0, v12
	v_add_f32_e32 v13, 1.0, v13
	v_rcp_f32_e32 v12, v12
	v_rcp_f32_e32 v13, v13
	v_cvt_pk_bf16_f32 v10, v10, v11
	v_pk_mul_f32 v[8:9], v[12:13], v[8:9]
	s_nop 0
	v_cvt_pk_bf16_f32 v11, v8, v9
	global_store_dwordx2 v[34:35], v[10:11], off offset:192
	v_lshlrev_b32_e32 v12, 16, v70
	v_and_b32_e32 v13, 0xffff0000, v70
	v_mul_f32_e32 v12, 0xbfb8aa3b, v12
	v_mul_f32_e32 v13, 0xbfb8aa3b, v13
	v_exp_f32_e32 v12, v12
	v_exp_f32_e32 v13, v13
	v_add_f32_e32 v12, 1.0, v12
	v_add_f32_e32 v13, 1.0, v13
	v_rcp_f32_e32 v12, v12
	v_rcp_f32_e32 v13, v13
	v_mov_b64_e32 v[8:9], v[234:235]
	v_mov_b64_e32 v[10:11], v[236:237]
	v_pk_mul_f32 v[6:7], v[8:9], v[6:7]
	v_lshlrev_b32_e32 v8, 16, v71
	v_and_b32_e32 v9, 0xffff0000, v71
	v_mul_f32_e32 v8, 0xbfb8aa3b, v8
	v_mul_f32_e32 v9, 0xbfb8aa3b, v9
	v_exp_f32_e32 v8, v8
	v_exp_f32_e32 v9, v9
	v_pk_mul_f32 v[4:5], v[10:11], v[4:5]
	v_pk_mul_f32 v[6:7], v[12:13], v[6:7]
	v_add_f32_e32 v8, 1.0, v8
	v_add_f32_e32 v9, 1.0, v9
	v_rcp_f32_e32 v8, v8
	v_rcp_f32_e32 v9, v9
	v_cvt_pk_bf16_f32 v6, v6, v7
	v_pk_mul_f32 v[4:5], v[8:9], v[4:5]
	s_nop 0
	v_cvt_pk_bf16_f32 v7, v4, v5
	global_store_dwordx2 v[34:35], v[6:7], off offset:224
	s_cbranch_vccz .LBB0_76
	v_readlane_b32 s14, v252, 7
	v_readlane_b32 s15, v252, 8
	s_load_dword s13, s[14:15], 0x0
	s_waitcnt lgkmcnt(0)
	s_add_i32 s12, s12, s13
	s_cmpk_gt_i32 s12, 0xff
	s_cbranch_scc0 .LBB0_73

.LBB0_217:
	s_lshl_b32 s5, s4, 8
	s_and_b32 s10, s5, 0x1f00
	s_ashr_i32 s5, s4, 31
	s_lshl_b64 s[8:9], s[4:5], 16
	s_waitcnt vmcnt(13)
	v_lshl_add_u64 v[12:13], v[36:37], 0, s[8:9]
	v_lshl_add_u64 v[8:9], v[44:45], 2, v[12:13]
	v_lshl_add_u64 v[68:69], v[46:47], 2, v[12:13]
	v_lshl_add_u64 v[70:71], v[48:49], 2, v[12:13]
	v_lshl_add_u64 v[72:73], v[50:51], 2, v[12:13]
	global_load_dwordx4 v[4:7], v[8:9], off offset:16
	global_load_dwordx4 v[14:17], v[8:9], off
	global_load_dwordx4 v[18:21], v[68:69], off offset:16
	global_load_dwordx4 v[22:25], v[68:69], off
	global_load_dwordx4 v[26:29], v[70:71], off offset:16
	global_load_dwordx4 v[30:33], v[70:71], off
	global_load_dwordx4 v[74:77], v[72:73], off offset:16
	global_load_dwordx4 v[78:81], v[72:73], off
	s_barrier
	s_ashr_i32 s6, s4, 7
	s_ashr_i32 s7, s6, 31
	s_lshl_b64 s[6:7], s[6:7], 13
	s_lshl_b32 s5, s4, 2
	s_or_b32 s6, s6, s10
	s_and_b32 s5, s5, 0x180
	v_lshl_add_u64 v[54:55], s[6:7], 0, v[0:1]
	v_lshl_add_u64 v[58:59], v[40:41], 0, s[6:7]
	s_lshl_b32 s6, s5, 2
	s_mov_b32 s7, s21
	v_lshl_add_u64 v[60:61], v[42:43], 0, s[6:7]
	v_readlane_b32 s6, v254, 50
	s_lshl_b32 s20, s5, 1
	v_readlane_b32 s7, v254, 51
	v_lshl_add_u64 v[56:57], v[38:39], 0, s[20:21]
	v_lshl_add_u64 v[64:65], v[52:53], 0, s[20:21]
	s_mov_b64 s[8:9], 0
	s_movk_i32 s12, 0x1c00
	s_waitcnt vmcnt(6)
	v_cvt_pk_bf16_f32 v8, v14, v15
	v_cvt_pk_bf16_f32 v9, v16, v17
	v_cvt_pk_bf16_f32 v10, v4, v5
	v_cvt_pk_bf16_f32 v11, v6, v7
	ds_write_b128 v93, v[8:11]
	s_waitcnt vmcnt(4)
	v_cvt_pk_bf16_f32 v82, v22, v23
	v_cvt_pk_bf16_f32 v83, v24, v25
	v_cvt_pk_bf16_f32 v84, v18, v19
	v_cvt_pk_bf16_f32 v85, v20, v21
	ds_write_b128 v93, v[82:85] offset:8704
	s_waitcnt vmcnt(2)
	v_cvt_pk_bf16_f32 v14, v30, v31
	v_cvt_pk_bf16_f32 v15, v32, v33
	v_cvt_pk_bf16_f32 v16, v26, v27
	v_cvt_pk_bf16_f32 v17, v28, v29
	ds_write_b128 v93, v[14:17] offset:17408
	s_waitcnt vmcnt(0)
	v_cvt_pk_bf16_f32 v18, v78, v79
	v_cvt_pk_bf16_f32 v19, v80, v81
	v_cvt_pk_bf16_f32 v20, v74, v75
	v_cvt_pk_bf16_f32 v21, v76, v77
	ds_write_b128 v93, v[18:21] offset:26112
	v_or_b32_e32 v4, s5, v88
	v_lshlrev_b32_e32 v2, 2, v4
	v_lshl_add_u64 v[62:63], s[0:1], 0, v[2:3]
	global_load_dwordx4 v[184:187], v[62:63], off
	global_load_dwordx4 v[188:191], v[62:63], off offset:64
	global_load_dwordx4 v[192:195], v[62:63], off offset:128
	global_load_dwordx4 v[196:199], v[62:63], off offset:192
	global_load_dwordx4 v[200:203], v[62:63], off offset:256
	global_load_dwordx4 v[204:207], v[62:63], off offset:320
	global_load_dwordx4 v[230:233], v[62:63], off offset:384
	global_load_dwordx4 v[234:237], v[62:63], off offset:448
	v_lshlrev_b32_e32 v2, 1, v4
	v_lshl_add_u64 v[66:67], s[6:7], 0, v[2:3]
	s_mov_b64 s[6:7], -1
.LBB0_218:
	v_lshl_add_u64 v[4:5], v[54:55], 0, s[8:9]
	v_mad_u64_u32 v[8:9], s[10:11], v4, s12, v[56:57]
	v_mov_b32_e32 v2, v9
	v_mad_u64_u32 v[10:11], s[10:11], v5, s12, v[2:3]
	v_mov_b32_e32 v9, v10
	s_mov_b32 s5, 0x38000
	v_add_co_u32_e32 v114, vcc, s5, v8
	s_mov_b32 s5, 0x70000
	s_nop 0
	v_addc_co_u32_e32 v115, vcc, 0, v10, vcc
	v_add_co_u32_e32 v116, vcc, s5, v8
	s_mov_b32 s5, 0xa8000
	s_nop 0
	v_addc_co_u32_e32 v117, vcc, 0, v10, vcc
	v_add_co_u32_e32 v118, vcc, s5, v8
	s_nop 1
	v_addc_co_u32_e32 v119, vcc, 0, v10, vcc
	global_load_dwordx4 v[120:123], v[8:9], off
	global_load_dwordx4 v[124:127], v[114:115], off
	global_load_dwordx4 v[128:131], v[116:117], off
	global_load_dwordx4 v[132:135], v[118:119], off
	v_lshl_add_u64 v[4:5], v[58:59], 0, s[8:9]
	v_mad_u64_u32 v[68:69], s[8:9], v4, s12, v[64:65]
	v_mov_b32_e32 v2, v69
	v_lshlrev_b64 v[84:85], 11, v[4:5]
	v_mad_u64_u32 v[4:5], s[8:9], v5, s12, v[2:3]
	v_lshl_add_u64 v[32:33], v[60:61], 0, v[84:85]
	v_mov_b32_e32 v69, v4
	global_load_dwordx4 v[24:27], v[32:33], off
	global_load_dwordx2 v[86:87], v[68:69], off offset:3072
	global_load_dwordx4 v[28:31], v[32:33], off offset:64
	global_load_dwordx2 v[80:81], v[68:69], off offset:3104
	global_load_dwordx4 v[20:23], v[32:33], off offset:128
	global_load_dwordx2 v[78:79], v[68:69], off offset:3136
	global_load_dwordx4 v[12:15], v[32:33], off offset:192
	global_load_dwordx2 v[76:77], v[68:69], off offset:3168
	global_load_dwordx4 v[16:19], v[32:33], off offset:256
	global_load_dwordx2 v[74:75], v[68:69], off offset:3200
	global_load_dwordx4 v[8:11], v[32:33], off offset:320
	global_load_dwordx2 v[72:73], v[68:69], off offset:3232
	global_load_dwordx4 v[4:7], v[32:33], off offset:384
	global_load_dwordx2 v[70:71], v[68:69], off offset:3264
	s_nop 0
	global_load_dwordx4 v[32:35], v[32:33], off offset:448
	s_nop 0
	global_load_dwordx2 v[68:69], v[68:69], off offset:3296
	s_waitcnt lgkmcnt(0)
	s_barrier
	s_waitcnt vmcnt(19)
	ds_write_b128 v93, v[120:123] offset:34816
	s_waitcnt vmcnt(18)
	ds_write_b128 v93, v[124:127] offset:43520
	s_waitcnt vmcnt(17)
	ds_write_b128 v93, v[128:131] offset:52224
	s_waitcnt vmcnt(16)
	ds_write_b128 v93, v[132:135] offset:60928
	s_waitcnt lgkmcnt(0)
	s_barrier
	ds_read_b128 v[94:97], v91 offset:34816
	ds_read_b128 v[98:101], v91 offset:34880
	ds_read_b128 v[102:105], v91 offset:34944
	ds_read_b128 v[106:109], v91 offset:35008
	ds_read_b128 v[110:113], v92
	ds_read_b128 v[114:117], v92 offset:64
	ds_read_b128 v[118:121], v92 offset:4416
	s_waitcnt lgkmcnt(2)
	v_mfma_f32_16x16x32_bf16 v[110:113], v[110:113], v[94:97], 0
	ds_read_b128 v[122:125], v92 offset:8768
	ds_read_b128 v[126:129], v92 offset:13120
	ds_read_b128 v[130:133], v92 offset:17472
	s_waitcnt lgkmcnt(4)
	v_mfma_f32_16x16x32_bf16 v[110:113], v[114:117], v[98:101], v[110:113]
	ds_read_b128 v[114:117], v92 offset:128
	s_mov_b64 s[8:9], 0x80
	ds_read_b128 v[134:137], v92 offset:21824
	s_waitcnt lgkmcnt(1)
	v_mfma_f32_16x16x32_bf16 v[110:113], v[114:117], v[102:105], v[110:113]
	ds_read_b128 v[114:117], v92 offset:192
	ds_read_b128 v[138:141], v92 offset:26176
	s_waitcnt lgkmcnt(1)
	v_mfma_f32_16x16x32_bf16 v[110:113], v[114:117], v[106:109], v[110:113]
	ds_read_b128 v[114:117], v92 offset:4352
	s_waitcnt vmcnt(15)
	s_nop 5
	v_pk_add_f32 v[24:25], v[24:25], v[110:111]
	s_waitcnt lgkmcnt(0)
	v_mfma_f32_16x16x32_bf16 v[114:117], v[114:117], v[94:97], 0
	v_mfma_f32_16x16x32_bf16 v[114:117], v[118:121], v[98:101], v[114:117]
	ds_read_b128 v[118:121], v92 offset:4480
	s_waitcnt lgkmcnt(0)
	v_mfma_f32_16x16x32_bf16 v[114:117], v[118:121], v[102:105], v[114:117]
	ds_read_b128 v[118:121], v92 offset:4544
	s_waitcnt lgkmcnt(0)
	v_mfma_f32_16x16x32_bf16 v[114:117], v[118:121], v[106:109], v[114:117]
	ds_read_b128 v[118:121], v92 offset:8704
	s_waitcnt vmcnt(13)
	s_nop 5
	v_pk_add_f32 v[82:83], v[28:29], v[114:115]
	s_waitcnt lgkmcnt(0)
	v_mfma_f32_16x16x32_bf16 v[118:121], v[118:121], v[94:97], 0
	v_add_f32_e64 v30, v30, v116
	v_add_f32_e64 v31, v31, v117
	v_mov_b32_e32 v28, v25
	v_mov_b32_e32 v29, v83
	v_mfma_f32_16x16x32_bf16 v[118:121], v[122:125], v[98:101], v[118:121]
	ds_read_b128 v[122:125], v92 offset:8832
	v_pk_mul_f32 v[28:29], v[28:29], v[28:29]
	s_waitcnt lgkmcnt(0)
	v_mfma_f32_16x16x32_bf16 v[118:121], v[122:125], v[102:105], v[118:121]
	ds_read_b128 v[122:125], v92 offset:8896
	s_waitcnt lgkmcnt(0)
	v_mfma_f32_16x16x32_bf16 v[118:121], v[122:125], v[106:109], v[118:121]
	ds_read_b128 v[122:125], v92 offset:13056
	s_waitcnt lgkmcnt(0)
	v_mfma_f32_16x16x32_bf16 v[122:125], v[122:125], v[94:97], 0
	v_mfma_f32_16x16x32_bf16 v[122:125], v[126:129], v[98:101], v[122:125]
	ds_read_b128 v[126:129], v92 offset:13184
	s_waitcnt lgkmcnt(0)
	v_mfma_f32_16x16x32_bf16 v[122:125], v[126:129], v[102:105], v[122:125]
	ds_read_b128 v[126:129], v92 offset:13248
	s_waitcnt lgkmcnt(0)
	v_mfma_f32_16x16x32_bf16 v[122:125], v[126:129], v[106:109], v[122:125]
	ds_read_b128 v[126:129], v92 offset:17408
	s_waitcnt lgkmcnt(0)
	v_mfma_f32_16x16x32_bf16 v[126:129], v[126:129], v[94:97], 0
	v_mfma_f32_16x16x32_bf16 v[126:129], v[130:133], v[98:101], v[126:129]
	ds_read_b128 v[130:133], v92 offset:17536
	s_waitcnt lgkmcnt(0)
	v_mfma_f32_16x16x32_bf16 v[126:129], v[130:133], v[102:105], v[126:129]
	ds_read_b128 v[130:133], v92 offset:17600
	s_waitcnt lgkmcnt(0)
	v_mfma_f32_16x16x32_bf16 v[126:129], v[130:133], v[106:109], v[126:129]
	ds_read_b128 v[130:133], v92 offset:21760
	s_waitcnt vmcnt(7)
	s_nop 5
	v_pk_add_f32 v[16:17], v[16:17], v[126:127]
	s_waitcnt lgkmcnt(0)
	v_mfma_f32_16x16x32_bf16 v[130:133], v[130:133], v[94:97], 0
	v_mul_f32_e32 v2, v16, v16
	v_pk_add_f32 v[18:19], v[18:19], v[128:129]
	v_mfma_f32_16x16x32_bf16 v[130:133], v[134:137], v[98:101], v[130:133]
	ds_read_b128 v[134:137], v92 offset:21888
	s_waitcnt lgkmcnt(0)
	v_mfma_f32_16x16x32_bf16 v[130:133], v[134:137], v[102:105], v[130:133]
	ds_read_b128 v[134:137], v92 offset:21952
	s_waitcnt lgkmcnt(0)
	v_mfma_f32_16x16x32_bf16 v[130:133], v[134:137], v[106:109], v[130:133]
	ds_read_b128 v[134:137], v92 offset:26112
	s_waitcnt lgkmcnt(0)
	v_mfma_f32_16x16x32_bf16 v[134:137], v[134:137], v[94:97], 0
	v_mfma_f32_16x16x32_bf16 v[134:137], v[138:141], v[98:101], v[134:137]
	ds_read_b128 v[138:141], v92 offset:26240
	s_waitcnt lgkmcnt(0)
	v_mfma_f32_16x16x32_bf16 v[134:137], v[138:141], v[102:105], v[134:137]
	ds_read_b128 v[138:141], v92 offset:26304
	s_waitcnt lgkmcnt(0)
	v_mfma_f32_16x16x32_bf16 v[134:137], v[138:141], v[106:109], v[134:137]
	ds_read_b128 v[138:141], v92 offset:30464
	s_waitcnt lgkmcnt(0)
	v_mfma_f32_16x16x32_bf16 v[94:97], v[138:141], v[94:97], 0
	ds_read_b128 v[138:141], v92 offset:30528
	s_waitcnt lgkmcnt(0)
	v_mfma_f32_16x16x32_bf16 v[94:97], v[138:141], v[98:101], v[94:97]
	ds_read_b128 v[98:101], v92 offset:30592
	s_waitcnt lgkmcnt(0)
	v_mfma_f32_16x16x32_bf16 v[94:97], v[98:101], v[102:105], v[94:97]
	ds_read_b128 v[98:101], v92 offset:30656
	v_mul_f32_e32 v104, v17, v17
	v_mul_f32_e32 v105, v18, v18
	s_waitcnt lgkmcnt(0)
	v_mfma_f32_16x16x32_bf16 v[94:97], v[98:101], v[106:109], v[94:97]
	v_add_f32_e64 v98, v26, v112
	v_add_f32_e64 v99, v27, v113
	v_mov_b32_e32 v26, v24
	v_mov_b32_e32 v27, v82
	v_mov_b32_e32 v100, v99
	v_mov_b32_e32 v101, v31
	v_pk_fma_f32 v[26:27], v[26:27], v[26:27], v[28:29]
	v_mov_b32_e32 v28, v98
	v_mov_b32_e32 v29, v30
	v_pk_mul_f32 v[100:101], v[100:101], v[100:101]
	v_mul_f32_e32 v106, v19, v19
	v_pk_fma_f32 v[28:29], v[28:29], v[28:29], v[100:101]
	s_nop 0
	v_pk_add_f32 v[100:101], v[26:27], v[28:29]
	v_pk_add_f32 v[26:27], v[22:23], v[120:121]
	v_pk_add_f32 v[28:29], v[20:21], v[118:119]
	v_pk_mul_f32 v[20:21], v[26:27], v[26:27]
	v_pk_mul_f32 v[22:23], v[28:29], v[28:29]
	s_nop 0
	v_pk_mov_b32 v[102:103], v[22:23], v[20:21] op_sel:[1,0]
	v_mov_b32_e32 v23, v21
	v_pk_add_f32 v[102:103], v[102:103], v[22:23]
	v_pk_add_f32 v[20:21], v[14:15], v[124:125]
	v_pk_add_f32 v[22:23], v[12:13], v[122:123]
	v_pk_add_f32 v[12:13], v[100:101], v[100:101] op_sel:[0,1] op_sel_hi:[1,0]
	v_pk_add_f32 v[14:15], v[102:103], v[102:103] op_sel:[0,1] op_sel_hi:[1,0]
	v_mov_b32_e32 v13, v2
	v_mov_b32_e32 v15, v104
	v_mul_f32_e32 v2, v23, v23
	v_pk_add_f32 v[12:13], v[12:13], v[14:15]
	v_pk_fma_f32 v[14:15], v[22:23], v[22:23], v[2:3] op_sel_hi:[1,1,0]
	v_mul_f32_e32 v2, v21, v21
	v_pk_fma_f32 v[100:101], v[20:21], v[20:21], v[2:3] op_sel_hi:[1,1,0]
	v_mov_b32_e32 v15, v105
	v_mov_b32_e32 v101, v106
	v_pk_add_f32 v[14:15], v[14:15], v[100:101]
	s_nop 0
	v_pk_add_f32 v[100:101], v[12:13], v[14:15]
	s_waitcnt vmcnt(5)
	v_pk_add_f32 v[12:13], v[10:11], v[132:133]
	v_pk_add_f32 v[14:15], v[8:9], v[130:131]
	v_pk_mul_f32 v[8:9], v[12:13], v[12:13]
	v_pk_mul_f32 v[10:11], v[14:15], v[14:15]
	s_nop 0
	v_pk_mov_b32 v[102:103], v[10:11], v[8:9] op_sel:[1,0]
	v_mov_b32_e32 v11, v9
	v_pk_add_f32 v[102:103], v[102:103], v[10:11]
	s_waitcnt vmcnt(3)
	v_pk_add_f32 v[8:9], v[6:7], v[136:137]
	s_waitcnt vmcnt(1)
	v_pk_add_f32 v[6:7], v[32:33], v[94:95]
	v_pk_add_f32 v[10:11], v[4:5], v[134:135]
	v_pk_add_f32 v[4:5], v[34:35], v[96:97]
	v_mul_f32_e32 v2, v6, v6
	v_mul_f32_e32 v94, v7, v7
	v_pk_add_f32 v[32:33], v[100:101], v[100:101] op_sel:[0,1] op_sel_hi:[1,0]
	v_pk_add_f32 v[34:35], v[102:103], v[102:103] op_sel:[0,1] op_sel_hi:[1,0]
	v_mov_b32_e32 v33, v2
	v_mov_b32_e32 v35, v94
	v_mul_f32_e32 v2, v11, v11
	v_mul_f32_e32 v95, v4, v4
	v_pk_add_f32 v[32:33], v[32:33], v[34:35]
	v_pk_fma_f32 v[34:35], v[10:11], v[10:11], v[2:3] op_sel_hi:[1,1,0]
	v_mul_f32_e32 v2, v9, v9
	v_mul_f32_e32 v96, v5, v5
	v_mov_b32_e32 v35, v95
	v_pk_fma_f32 v[94:95], v[8:9], v[8:9], v[2:3] op_sel_hi:[1,1,0]
	s_nop 0
	v_mov_b32_e32 v95, v96
	v_pk_add_f32 v[34:35], v[34:35], v[94:95]
	v_lshlrev_b32_e32 v94, 16, v86
	v_pk_add_f32 v[32:33], v[32:33], v[34:35]
	v_and_b32_e32 v95, 0xffff0000, v86
	v_add_f32_e32 v2, v32, v33
	ds_bpermute_b32 v32, v89, v2
	v_mul_f32_e32 v86, 0xbfb8aa3b, v94
	v_exp_f32_e32 v86, v86
	s_waitcnt lgkmcnt(0)
	v_add_f32_e32 v2, v2, v32
	ds_bpermute_b32 v32, v90, v2
	v_add_f32_e32 v86, 1.0, v86
	v_rcp_f32_e32 v96, v86
	s_waitcnt lgkmcnt(0)
	v_add_f32_e32 v2, v2, v32
	v_fmamk_f32 v2, v2, 0x3c000000, v172
	v_cmp_gt_f32_e32 vcc, s33, v2
	v_mul_f32_e32 v32, 0x4b800000, v2
	s_nop 0
	v_cndmask_b32_e32 v2, v2, v32, vcc
	v_rsq_f32_e32 v2, v2
	s_nop 0
	v_mul_f32_e32 v32, 0x45800000, v2
	v_cndmask_b32_e32 v2, v2, v32, vcc
	v_pk_mul_f32 v[24:25], v[24:25], v[2:3] op_sel_hi:[1,0]
	v_pk_mul_f32 v[82:83], v[82:83], v[2:3] op_sel_hi:[1,0]
	v_pk_mul_f32 v[30:31], v[30:31], v[2:3] op_sel_hi:[1,0]
	v_pk_mul_f32 v[28:29], v[28:29], v[2:3] op_sel_hi:[1,0]
	v_pk_mul_f32 v[26:27], v[26:27], v[2:3] op_sel_hi:[1,0]
	v_pk_mul_f32 v[22:23], v[22:23], v[2:3] op_sel_hi:[1,0]
	v_pk_mul_f32 v[20:21], v[20:21], v[2:3] op_sel_hi:[1,0]
	v_pk_mul_f32 v[16:17], v[16:17], v[2:3] op_sel_hi:[1,0]
	v_pk_mul_f32 v[18:19], v[18:19], v[2:3] op_sel_hi:[1,0]
	v_pk_mul_f32 v[14:15], v[14:15], v[2:3] op_sel_hi:[1,0]
	v_pk_mul_f32 v[12:13], v[12:13], v[2:3] op_sel_hi:[1,0]
	v_pk_mul_f32 v[10:11], v[10:11], v[2:3] op_sel_hi:[1,0]
	v_pk_mul_f32 v[8:9], v[8:9], v[2:3] op_sel_hi:[1,0]
	v_pk_mul_f32 v[6:7], v[6:7], v[2:3] op_sel_hi:[1,0]
	v_pk_mul_f32 v[4:5], v[4:5], v[2:3] op_sel_hi:[1,0]
	s_andn2_b64 vcc, exec, s[6:7]
	s_mov_b64 s[6:7], 0
	s_waitcnt vmcnt(0)
	v_mov_b64_e32 v[32:33], v[184:185]
	v_mov_b64_e32 v[34:35], v[186:187]
	v_pk_mul_f32 v[24:25], v[32:33], v[24:25]
	v_mul_f32_e32 v32, 0xbfb8aa3b, v95
	v_exp_f32_e32 v32, v32
	s_nop 0
	v_add_f32_e32 v32, 1.0, v32
	v_rcp_f32_e32 v97, v32
	s_nop 0
	v_pk_mul_f32 v[32:33], v[96:97], v[94:95]
	s_nop 0
	v_pk_mul_f32 v[24:25], v[32:33], v[24:25]
	v_lshlrev_b32_e32 v32, 16, v87
	v_and_b32_e32 v33, 0xffff0000, v87
	v_mul_f32_e32 v86, 0xbfb8aa3b, v32
	v_mul_f32_e32 v87, 0xbfb8aa3b, v33
	v_exp_f32_e32 v86, v86
	v_exp_f32_e32 v87, v87
	v_pk_mul_f32 v[94:95], v[98:99], v[2:3] op_sel_hi:[1,0]
	v_add_f32_e32 v86, 1.0, v86
	v_add_f32_e32 v87, 1.0, v87
	v_rcp_f32_e32 v86, v86
	v_rcp_f32_e32 v87, v87
	v_pk_mul_f32 v[34:35], v[34:35], v[94:95]
	v_pk_mul_f32 v[32:33], v[86:87], v[32:33]
	s_nop 0
	v_pk_mul_f32 v[34:35], v[32:33], v[34:35]
	v_cvt_pk_bf16_f32 v32, v24, v25
	v_cvt_pk_bf16_f32 v33, v34, v35
	v_lshl_add_u64 v[24:25], v[66:67], 0, v[84:85]
	global_store_dwordx2 v[24:25], v[32:33], off
	v_lshlrev_b32_e32 v84, 16, v80
	v_and_b32_e32 v85, 0xffff0000, v80
	v_mul_f32_e32 v80, 0xbfb8aa3b, v84
	v_exp_f32_e32 v80, v80
	v_mov_b64_e32 v[32:33], v[188:189]
	v_mov_b64_e32 v[34:35], v[190:191]
	v_pk_mul_f32 v[32:33], v[32:33], v[82:83]
	v_add_f32_e32 v80, 1.0, v80
	v_rcp_f32_e32 v86, v80
	v_mul_f32_e32 v80, 0xbfb8aa3b, v85
	v_exp_f32_e32 v80, v80
	v_pk_mul_f32 v[30:31], v[34:35], v[30:31]
	v_add_f32_e32 v80, 1.0, v80
	v_rcp_f32_e32 v87, v80
	v_lshlrev_b32_e32 v80, 16, v81
	v_and_b32_e32 v81, 0xffff0000, v81
	v_mul_f32_e32 v34, 0xbfb8aa3b, v81
	v_pk_mul_f32 v[82:83], v[86:87], v[84:85]
	v_exp_f32_e32 v34, v34
	v_pk_mul_f32 v[32:33], v[82:83], v[32:33]
	v_mul_f32_e32 v82, 0xbfb8aa3b, v80
	v_exp_f32_e32 v82, v82
	v_add_f32_e32 v34, 1.0, v34
	v_rcp_f32_e32 v83, v34
	v_cvt_pk_bf16_f32 v32, v32, v33
	v_add_f32_e32 v82, 1.0, v82
	v_rcp_f32_e32 v82, v82
	s_nop 0
	v_pk_mul_f32 v[34:35], v[82:83], v[80:81]
	s_nop 0
	v_pk_mul_f32 v[30:31], v[34:35], v[30:31]
	v_lshlrev_b32_e32 v34, 16, v78
	v_cvt_pk_bf16_f32 v33, v30, v31
	global_store_dwordx2 v[24:25], v[32:33], off offset:32
	v_and_b32_e32 v35, 0xffff0000, v78
	v_mul_f32_e32 v78, 0xbfb8aa3b, v34
	v_exp_f32_e32 v78, v78
	v_mov_b64_e32 v[30:31], v[192:193]
	v_mov_b64_e32 v[32:33], v[194:195]
	v_pk_mul_f32 v[28:29], v[30:31], v[28:29]
	v_mul_f32_e32 v30, 0xbfb8aa3b, v35
	v_exp_f32_e32 v30, v30
	v_add_f32_e32 v78, 1.0, v78
	v_rcp_f32_e32 v80, v78
	v_pk_mul_f32 v[26:27], v[32:33], v[26:27]
	v_add_f32_e32 v30, 1.0, v30
	v_rcp_f32_e32 v81, v30
	s_nop 0
	v_pk_mul_f32 v[30:31], v[80:81], v[34:35]
	s_nop 0
	v_pk_mul_f32 v[28:29], v[30:31], v[28:29]
	v_lshlrev_b32_e32 v30, 16, v79
	v_and_b32_e32 v31, 0xffff0000, v79
	v_mul_f32_e32 v34, 0xbfb8aa3b, v30
	v_mul_f32_e32 v32, 0xbfb8aa3b, v31
	v_exp_f32_e32 v34, v34
	v_exp_f32_e32 v32, v32
	v_cvt_pk_bf16_f32 v28, v28, v29
	v_add_f32_e32 v34, 1.0, v34
	v_add_f32_e32 v32, 1.0, v32
	v_rcp_f32_e32 v34, v34
	v_rcp_f32_e32 v35, v32
	s_nop 0
	v_pk_mul_f32 v[30:31], v[34:35], v[30:31]
	s_nop 0
	v_pk_mul_f32 v[26:27], v[30:31], v[26:27]
	v_lshlrev_b32_e32 v30, 16, v76
	v_cvt_pk_bf16_f32 v29, v26, v27
	global_store_dwordx2 v[24:25], v[28:29], off offset:64
	v_and_b32_e32 v31, 0xffff0000, v76
	v_mul_f32_e32 v32, 0xbfb8aa3b, v30
	v_exp_f32_e32 v32, v32
	v_mov_b64_e32 v[26:27], v[196:197]
	v_mov_b64_e32 v[28:29], v[198:199]
	v_pk_mul_f32 v[22:23], v[26:27], v[22:23]
	v_mul_f32_e32 v26, 0xbfb8aa3b, v31
	v_exp_f32_e32 v26, v26
	v_add_f32_e32 v32, 1.0, v32
	v_rcp_f32_e32 v32, v32
	v_pk_mul_f32 v[20:21], v[28:29], v[20:21]
	v_add_f32_e32 v26, 1.0, v26
	v_rcp_f32_e32 v33, v26
	s_nop 0
	v_pk_mul_f32 v[26:27], v[32:33], v[30:31]
	s_nop 0
	v_pk_mul_f32 v[22:23], v[26:27], v[22:23]
	v_lshlrev_b32_e32 v26, 16, v77
	v_and_b32_e32 v27, 0xffff0000, v77
	v_mul_f32_e32 v30, 0xbfb8aa3b, v26
	v_mul_f32_e32 v28, 0xbfb8aa3b, v27
	v_exp_f32_e32 v30, v30
	v_exp_f32_e32 v28, v28
	v_cvt_pk_bf16_f32 v22, v22, v23
	v_add_f32_e32 v30, 1.0, v30
	v_add_f32_e32 v28, 1.0, v28
	v_rcp_f32_e32 v30, v30
	v_rcp_f32_e32 v31, v28
	s_nop 0
	v_pk_mul_f32 v[26:27], v[30:31], v[26:27]
	s_nop 0
	v_pk_mul_f32 v[20:21], v[26:27], v[20:21]
	v_lshlrev_b32_e32 v26, 16, v74
	v_cvt_pk_bf16_f32 v23, v20, v21
	global_store_dwordx2 v[24:25], v[22:23], off offset:96
	v_and_b32_e32 v27, 0xffff0000, v74
	v_mul_f32_e32 v28, 0xbfb8aa3b, v26
	v_exp_f32_e32 v28, v28
	v_mov_b64_e32 v[20:21], v[200:201]
	v_mov_b64_e32 v[22:23], v[202:203]
	v_pk_mul_f32 v[16:17], v[20:21], v[16:17]
	v_mul_f32_e32 v20, 0xbfb8aa3b, v27
	v_exp_f32_e32 v20, v20
	v_add_f32_e32 v28, 1.0, v28
	v_rcp_f32_e32 v28, v28
	v_pk_mul_f32 v[18:19], v[22:23], v[18:19]
	v_add_f32_e32 v20, 1.0, v20
	v_rcp_f32_e32 v29, v20
	s_nop 0
	v_pk_mul_f32 v[20:21], v[28:29], v[26:27]
	s_nop 0
	v_pk_mul_f32 v[16:17], v[20:21], v[16:17]
	v_lshlrev_b32_e32 v20, 16, v75
	v_and_b32_e32 v21, 0xffff0000, v75
	v_mul_f32_e32 v26, 0xbfb8aa3b, v20
	v_mul_f32_e32 v22, 0xbfb8aa3b, v21
	v_exp_f32_e32 v26, v26
	v_exp_f32_e32 v22, v22
	v_cvt_pk_bf16_f32 v16, v16, v17
	v_add_f32_e32 v26, 1.0, v26
	v_add_f32_e32 v22, 1.0, v22
	v_rcp_f32_e32 v26, v26
	v_rcp_f32_e32 v27, v22
	s_nop 0
	v_pk_mul_f32 v[20:21], v[26:27], v[20:21]
	s_nop 0
	v_pk_mul_f32 v[18:19], v[20:21], v[18:19]
	v_lshlrev_b32_e32 v20, 16, v72
	v_cvt_pk_bf16_f32 v17, v18, v19
	global_store_dwordx2 v[24:25], v[16:17], off offset:128
	v_and_b32_e32 v21, 0xffff0000, v72
	v_mul_f32_e32 v22, 0xbfb8aa3b, v20
	v_exp_f32_e32 v22, v22
	v_mov_b64_e32 v[16:17], v[204:205]
	v_mov_b64_e32 v[18:19], v[206:207]
	v_pk_mul_f32 v[14:15], v[16:17], v[14:15]
	v_mul_f32_e32 v16, 0xbfb8aa3b, v21
	v_exp_f32_e32 v16, v16
	v_add_f32_e32 v22, 1.0, v22
	v_rcp_f32_e32 v22, v22
	v_pk_mul_f32 v[12:13], v[18:19], v[12:13]
	v_add_f32_e32 v16, 1.0, v16
	v_rcp_f32_e32 v23, v16
	s_nop 0
	v_pk_mul_f32 v[16:17], v[22:23], v[20:21]
	s_nop 0
	v_pk_mul_f32 v[14:15], v[16:17], v[14:15]
	v_lshlrev_b32_e32 v16, 16, v73
	v_and_b32_e32 v17, 0xffff0000, v73
	v_mul_f32_e32 v20, 0xbfb8aa3b, v16
	v_mul_f32_e32 v18, 0xbfb8aa3b, v17
	v_exp_f32_e32 v20, v20
	v_exp_f32_e32 v18, v18
	v_cvt_pk_bf16_f32 v14, v14, v15
	v_add_f32_e32 v20, 1.0, v20
	v_add_f32_e32 v18, 1.0, v18
	v_rcp_f32_e32 v20, v20
	v_rcp_f32_e32 v21, v18
	s_nop 0
	v_pk_mul_f32 v[16:17], v[20:21], v[16:17]
	s_nop 0
	v_pk_mul_f32 v[12:13], v[16:17], v[12:13]
	v_lshlrev_b32_e32 v16, 16, v70
	v_cvt_pk_bf16_f32 v15, v12, v13
	global_store_dwordx2 v[24:25], v[14:15], off offset:160
	v_and_b32_e32 v17, 0xffff0000, v70
	v_mul_f32_e32 v18, 0xbfb8aa3b, v16
	v_exp_f32_e32 v18, v18
	v_mov_b64_e32 v[12:13], v[230:231]
	v_mov_b64_e32 v[14:15], v[232:233]
	v_pk_mul_f32 v[10:11], v[12:13], v[10:11]
	v_mul_f32_e32 v12, 0xbfb8aa3b, v17
	v_exp_f32_e32 v12, v12
	v_add_f32_e32 v18, 1.0, v18
	v_rcp_f32_e32 v18, v18
	v_pk_mul_f32 v[8:9], v[14:15], v[8:9]
	v_add_f32_e32 v12, 1.0, v12
	v_rcp_f32_e32 v19, v12
	s_nop 0
	v_pk_mul_f32 v[12:13], v[18:19], v[16:17]
	s_nop 0
	v_pk_mul_f32 v[10:11], v[12:13], v[10:11]
	v_lshlrev_b32_e32 v12, 16, v71
	v_and_b32_e32 v13, 0xffff0000, v71
	v_mul_f32_e32 v16, 0xbfb8aa3b, v12
	v_mul_f32_e32 v14, 0xbfb8aa3b, v13
	v_exp_f32_e32 v16, v16
	v_exp_f32_e32 v14, v14
	v_cvt_pk_bf16_f32 v10, v10, v11
	v_add_f32_e32 v16, 1.0, v16
	v_add_f32_e32 v14, 1.0, v14
	v_rcp_f32_e32 v16, v16
	v_rcp_f32_e32 v17, v14
	s_nop 0
	v_pk_mul_f32 v[12:13], v[16:17], v[12:13]
	s_nop 0
	v_pk_mul_f32 v[8:9], v[12:13], v[8:9]
	v_lshlrev_b32_e32 v12, 16, v68
	v_cvt_pk_bf16_f32 v11, v8, v9
	global_store_dwordx2 v[24:25], v[10:11], off offset:192
	v_and_b32_e32 v13, 0xffff0000, v68
	v_mul_f32_e32 v14, 0xbfb8aa3b, v12
	v_exp_f32_e32 v14, v14
	v_mov_b64_e32 v[8:9], v[234:235]
	v_mov_b64_e32 v[10:11], v[236:237]
	v_pk_mul_f32 v[6:7], v[6:7], v[8:9]
	v_mul_f32_e32 v8, 0xbfb8aa3b, v13
	v_exp_f32_e32 v8, v8
	v_add_f32_e32 v14, 1.0, v14
	v_rcp_f32_e32 v14, v14
	v_pk_mul_f32 v[4:5], v[4:5], v[10:11]
	v_add_f32_e32 v8, 1.0, v8
	v_rcp_f32_e32 v15, v8
	s_nop 0
	v_pk_mul_f32 v[8:9], v[14:15], v[12:13]
	s_nop 0
	v_pk_mul_f32 v[6:7], v[8:9], v[6:7]
	v_lshlrev_b32_e32 v8, 16, v69
	v_and_b32_e32 v9, 0xffff0000, v69
	v_mul_f32_e32 v12, 0xbfb8aa3b, v8
	v_mul_f32_e32 v2, 0xbfb8aa3b, v9
	v_exp_f32_e32 v12, v12
	v_exp_f32_e32 v2, v2
	v_cvt_pk_bf16_f32 v6, v6, v7
	v_add_f32_e32 v12, 1.0, v12
	v_add_f32_e32 v2, 1.0, v2
	v_rcp_f32_e32 v12, v12
	v_rcp_f32_e32 v13, v2
	s_nop 0
	v_pk_mul_f32 v[8:9], v[12:13], v[8:9]
	s_nop 0
	v_pk_mul_f32 v[4:5], v[8:9], v[4:5]
	s_nop 0
	v_cvt_pk_bf16_f32 v7, v4, v5
	global_store_dwordx2 v[24:25], v[6:7], off offset:224
	s_cbranch_vccz .LBB0_218
	v_readlane_b32 s6, v252, 7
	v_readlane_b32 s7, v252, 8
	s_load_dword s5, s[6:7], 0x0
	s_waitcnt lgkmcnt(0)
	s_add_i32 s4, s4, s5
	s_cmpk_gt_i32 s4, 0xff
	s_cbranch_scc0 .LBB0_217
